# speedup vs baseline: 1.0360x; 1.0045x over previous
.LBB0_29:
	s_and_b64 vcc, exec, s[4:5]
	s_cbranch_vccz .LBB0_39
	s_cmpk_gt_i32 s78, 0xb15
	s_cbranch_scc1 .LBB0_39
	s_cmpk_lt_i32 s78, 0x116
	s_cbranch_scc1 .Lstag_ffn1
	s_sleep 127
	s_sleep 127
	s_sleep 127
	s_sleep 127
.Lstag_ffn1:
	v_readlane_b32 s2, v254, 1
	v_readlane_b32 s4, v254, 10
	v_readlane_b32 s3, v254, 2
	s_add_u32 s12, s2, 0x406c000
	v_readlane_b32 s5, v254, 11
	s_addc_u32 s13, s3, 0
	s_mul_hi_i32 s5, s4, 0xb00000
	s_mul_i32 s4, s4, 0xb00000
	s_add_u32 s4, s2, s4
	s_addc_u32 s5, s3, s5
	s_add_u32 s14, s4, 0x1f00000
	s_addc_u32 s15, s5, 0
	s_add_u32 s6, s2, 0xb52c000
	s_addc_u32 s7, s3, 0
	s_mov_b32 s16, s78
